# attention fast-loop head aligned to 64 bytes (.p2align 6, s_nop padding executed once per unit)
# baseline (speedup 1.0000x reference)
; #define LAS __attribute__((address_space(3)))
; __device__ __forceinline__ int v_st(int k, int c) { const int kk = k; return ((kk >> 3) * 4 + (c >> 5)) * 512 + ((kk & 7) * 32 + (c & 31)) * 2; }
; __device__ __forceinline__ int v_rd_base(int lane) { return ((lane & 3) << 3) | (((lane >> 2) & 3) << 6) | (((lane >> 4) & 1) << 5) | (((lane >> 5) & 1) << 8); }
; #define ABAR() asm volatile("s_waitcnt lgkmcnt(0)\n\ts_barrier" ::: "memory")
; #define SLOAD(i, k0) do { const bf16_t* vt_ = Vh + (size_t)(k0) * 512; const bf16_t* kt_ = KNh + (size_t)(k0) * 512; const bf16_t* rt_ = KRb + (size_t)(k0) * 32; \
;     sr_[i].vs = *reinterpret_cast<const bf16x8*>(vt_ + lo_kv); sr_[i].ks = *reinterpret_cast<const bf16x8*>(kt_ + lo_kv); sr_[i].kr = *reinterpret_cast<const s16x4*>(rt_ + lo_kr); } while (0)
; #define SWRITE(slot, i) do { *(bf16x8*)(V_lds + (slot) * SHM_V + vst) = sr_[i].vs; *(bf16x8*)(K_lds + (slot) * SHM_K + kst) = sr_[i].ks; *(s16x4*)(K_lds + (slot) * SHM_K + krst) = sr_[i].kr; } while (0)
; __device__ __forceinline__ void attn_unit(const bf16_t* __restrict__ Qb, const bf16_t* __restrict__ KNh, const bf16_t* __restrict__ KRb, const bf16_t* __restrict__ Vh, bf16_t* __restrict__ Ob, char* lds) {
;     ...
;   float mref = 0.f, l_reg = 0; f32x16 negm = {}; f32x16 o[2] = {}; bf16x8 qr[6];
;   const bf16_t* Qw = Qb + (long)(wid * QBLK + r32) * 768 + hi * 8;
; #pragma unroll
;   for (int d0 = 0; d0 < 6; ++d0) qr[d0] = *reinterpret_cast<const bf16x8*>(Qw + d0 * 16);
;   const int sr = tid >> 3, sc = (tid & 7) * 8, vst = v_st(sr, sc), kst = KSWZ(sr, sc * 2), krst = KSWZ(sr, 128 + (tid & 7) * 8);
;   const lds_cptr vb0 = (lds_cptr)(LAS char*)lds + v_rd_base(lane);
;   struct { bf16x8 vs, ks; s16x4 kr; } sr_[2];
;   const unsigned lo_kv = (unsigned)(sr * 512 + sc), lo_kr = (unsigned)(sr * 32 + (tid & 7) * 4);
;     ...
;   if (__builtin_amdgcn_readfirstlane(tid >> 6) >= 4) __builtin_amdgcn_s_setprio(1);
;   f32x16 pA0, pA1, pB0, pB1; float alA, alB; bf16x8 pa0, pa1, pa2, pa3; constexpr int NT = SEQ / KVBLK;
;   SLOAD(0, 0); SLOAD(1, KVBLK); asm volatile("s_waitcnt vmcnt(0)" ::: "memory"); SWRITE(0, 0); SWRITE(1, 1); SLOAD(0, 2 * KVBLK); ABAR();
.LBB0_738:
	s_xor_b64 s[34:35], s[30:31], -1
	s_lshr_b32 s91, s33, 3
	s_lshl_b64 s[62:63], s[42:43], 21
	s_add_u32 s44, s14, s62
	s_addc_u32 s45, s15, s63
	s_lshl_b32 s88, s41, 6
	s_lshl_b32 s41, s41, 7
	s_add_u32 s44, s44, s41
	s_addc_u32 s45, s45, 0
	s_lshl_b64 s[64:65], s[42:43], 17
	s_add_u32 s42, s24, s64
	v_readlane_b32 s43, v252, 36
	s_addc_u32 s43, s43, s65
	s_add_u32 s46, s25, s62
	s_addc_u32 s47, s97, s63
	s_add_u32 s46, s46, s41
	s_addc_u32 s47, s47, 0
	v_mov_b32_e32 v169, v153
	v_lshl_add_u64 v[52:53], s[46:47], 0, v[168:169]
	s_mov_b32 s89, 0x10000
	v_add_co_u32_e32 v8, vcc, s89, v52
	v_lshl_add_u64 v[50:51], s[44:45], 0, v[168:169]
	s_nop 0
	v_addc_co_u32_e32 v9, vcc, 0, v53, vcc
	v_add_co_u32_e32 v12, vcc, s89, v50
	global_load_dwordx4 v[0:3], v168, s[46:47]
	s_nop 0
	v_addc_co_u32_e32 v13, vcc, 0, v51, vcc
	global_load_dwordx4 v[4:7], v168, s[44:45]
	global_load_dwordx2 v[16:17], v170, s[42:43]
	s_nop 0
	global_load_dwordx4 v[8:11], v[8:9], off
	s_nop 0
	global_load_dwordx4 v[12:15], v[12:13], off
	v_mov_b32_e32 v171, v153
	v_lshl_add_u64 v[48:49], s[42:43], 0, v[170:171]
	v_add_co_u32_e32 v18, vcc, s70, v48
	v_add_u32_e32 v26, s85, v201
	s_nop 0
	v_addc_co_u32_e32 v19, vcc, 0, v49, vcc
	global_load_dwordx2 v[20:21], v[18:19], off offset:-4096
	v_add_co_u32_e32 v22, vcc, s67, v50
	s_waitcnt vmcnt(0)
	v_add_u32_e32 v27, s85, v202
	s_nop 0
	v_addc_co_u32_e32 v23, vcc, 0, v51, vcc
	v_add_co_u32_e32 v24, vcc, s67, v52
	v_add_u32_e32 v28, s82, v201
	s_nop 0
	v_addc_co_u32_e32 v25, vcc, 0, v53, vcc
	v_add_u32_e32 v29, s82, v202
	global_load_dwordx4 v[136:139], v[24:25], off
	global_load_dwordx4 v[140:143], v[22:23], off
	global_load_dwordx2 v[172:173], v[18:19], off
	v_add_u32_e32 v30, s85, v206
	v_add_co_u32_e32 v62, vcc, s84, v52
	v_add_u32_e32 v64, s85, v211
	s_nop 0
	v_addc_co_u32_e32 v63, vcc, 0, v53, vcc
	s_mov_b32 s41, s40
	s_mov_b32 s42, s40
	s_mov_b32 s43, s40
	s_mov_b32 s44, s40
	s_mov_b32 s45, s40
	s_mov_b32 s46, s40
	s_mov_b32 s47, s40
	s_mov_b32 s48, s40
	s_mov_b32 s49, s40
	s_mov_b32 s50, s40
	s_mov_b32 s51, s40
	s_mov_b32 s52, s40
	s_mov_b32 s53, s40
	s_mov_b32 s54, s40
	s_mov_b32 s55, s40
	s_mov_b32 s90, 1
	v_mov_b32_e32 v177, s65
	v_or_b32_e32 v176, s64, v154
	v_mov_b32_e32 v152, 0
	v_mov_b32_e32 v163, 1.0
	s_waitcnt vmcnt(7)
	ds_write_b128 v26, v[4:7]
	s_waitcnt vmcnt(6)
	ds_write_b64 v27, v[16:17]
	ds_write_b128 v204, v[0:3]
	s_waitcnt vmcnt(5)
	ds_write_b128 v204, v[8:11] offset:16384
	s_waitcnt vmcnt(4)
	ds_write_b128 v28, v[12:15]
	s_waitcnt vmcnt(3)
	ds_write_b64 v29, v[20:21]
	s_waitcnt lgkmcnt(0)
	s_barrier
; template <bool FIRST> __device__ __forceinline__ void partialSM(f32x16& p0, f32x16& p1, float& mref, f32x16& negm, float& alpha) {
;   constexpr float THRL = THR * 1.4426950408889634f;
;   float pmax = p0[0];
; #pragma unroll
;   for (int r = 1; r < 16; ++r) pmax = fmaxf(pmax, p0[r]);
; #pragma unroll
;   for (int r = 0; r < 16; ++r) pmax = fmaxf(pmax, p1[r]);
;   { auto rr = __builtin_amdgcn_permlane32_swap(__float_as_uint(pmax), __float_as_uint(pmax), false, false);
;     pmax = fmaxf(__uint_as_float(rr[0]), __uint_as_float(rr[1])); }
;   if (!FIRST && __builtin_expect(__all(pmax <= THRL), 1)) { alpha = 1.f; }
;   else { const float dl = FIRST ? pmax : fmaxf(pmax, 0.f); mref += dl; alpha = FIRST ? 1.f : __builtin_amdgcn_exp2f(-dl);
; #pragma unroll
;     for (int r = 0; r < 16; ++r) { p0[r] -= dl; p1[r] -= dl; }
;     const float nm = -mref;
; #pragma unroll
;     for (int r = 0; r < 16; ++r) negm[r] = nm; }
; #pragma unroll
;   for (int r = 0; r < 16; ++r) p0[r] = __builtin_amdgcn_exp2f(p0[r]);
; }
; __device__ __forceinline__ void finishSM(f32x16& p0, f32x16& p1, float alpha, float& l_reg, bf16x8& pa0, bf16x8& pa1, bf16x8& pa2, bf16x8& pa3) {
; #pragma unroll
;   for (int r = 0; r < 16; ++r) p1[r] = __builtin_amdgcn_exp2f(p1[r]);
;   float ps = 0;
; #pragma unroll
;   for (int r = 0; r < 16; ++r) ps += p0[r];
; #pragma unroll
;   for (int r = 0; r < 16; ++r) ps += p1[r];
;   { auto rr = __builtin_amdgcn_permlane32_swap(__float_as_uint(ps), __float_as_uint(ps), false, false);
;     ps = __uint_as_float(rr[0]) + __uint_as_float(rr[1]); }
;   l_reg = l_reg * alpha + ps;
;     ...
;   PK4(p0, 0, pa0); PK4(p0, 8, pa1); PK4(p1, 0, pa2); PK4(p1, 8, pa3);
;     ...
; }
; __device__ __forceinline__ void qkt(f32x16& p0, f32x16& p1, const char* Ks, const bf16x8* qr, const f32x16& negm, int r32, int hi) {
;   p0 = negm; p1 = negm;
; #pragma unroll
;   for (int d0 = 0; d0 < 6; ++d0) { int cb = (d0 * 16 + hi * 8) * 2;
;     bf16x8 b0 = *reinterpret_cast<const bf16x8*>(Ks + KSWZ(r32, cb));
;     bf16x8 b1 = *reinterpret_cast<const bf16x8*>(Ks + KSWZ(32 + r32, cb));
;     p0 = __builtin_amdgcn_mfma_f32_32x32x16_bf16(b0, qr[d0], p0, 0, 0, 0);
;     p1 = __builtin_amdgcn_mfma_f32_32x32x16_bf16(b1, qr[d0], p1, 0, 0, 0); }
; }
	ds_read_b128 v[0:3], v30
	ds_read_b128 v[4:7], v30 offset:8192
	s_waitcnt lgkmcnt(1)
	v_mfma_f32_32x32x16_bf16 v[32:47], v[0:3], v[132:135], 0
	v_add_u32_e32 v8, s85, v207
	s_waitcnt lgkmcnt(0)
	v_mfma_f32_32x32x16_bf16 v[16:31], v[4:7], v[132:135], 0
	ds_read_b128 v[0:3], v8
	ds_read_b128 v[4:7], v8 offset:8192
	v_add_u32_e32 v8, s85, v208
	s_waitcnt lgkmcnt(1)
	v_mfma_f32_32x32x16_bf16 v[32:47], v[0:3], v[128:131], v[32:47]
	s_waitcnt lgkmcnt(0)
	v_mfma_f32_32x32x16_bf16 v[16:31], v[4:7], v[128:131], v[16:31]
	ds_read_b128 v[0:3], v8
	ds_read_b128 v[4:7], v8 offset:8192
	v_add_u32_e32 v8, s85, v209
	ds_read_b128 v[58:61], v64
	s_waitcnt lgkmcnt(2)
	v_mfma_f32_32x32x16_bf16 v[32:47], v[0:3], v[124:127], v[32:47]
	ds_read_b128 v[0:3], v8
	s_waitcnt lgkmcnt(2)
	v_mfma_f32_32x32x16_bf16 v[16:31], v[4:7], v[124:127], v[16:31]
	ds_read_b128 v[4:7], v8 offset:8192
	v_add_u32_e32 v8, s85, v210
	ds_read_b128 v[54:57], v8 offset:8192
	s_waitcnt lgkmcnt(2)
	v_mfma_f32_32x32x16_bf16 v[32:47], v[0:3], v[120:123], v[32:47]
	ds_read_b128 v[0:3], v8
	s_waitcnt lgkmcnt(2)
	v_mfma_f32_32x32x16_bf16 v[16:31], v[4:7], v[120:123], v[16:31]
	s_waitcnt lgkmcnt(1)
	v_mfma_f32_32x32x16_bf16 v[16:31], v[54:57], v[116:119], v[16:31]
	v_add_co_u32_e32 v54, vcc, s84, v50
	s_nop 1
	v_addc_co_u32_e32 v55, vcc, 0, v51, vcc
	v_add_co_u32_e32 v48, vcc, s80, v48
	ds_read_b128 v[50:53], v64 offset:8192
	s_nop 0
	v_addc_co_u32_e32 v49, vcc, 0, v49, vcc
	global_load_dwordx4 v[144:147], v[62:63], off
	global_load_dwordx4 v[148:151], v[54:55], off
	global_load_dwordx2 v[174:175], v[48:49], off
	s_waitcnt lgkmcnt(1)
	v_mfma_f32_32x32x16_bf16 v[32:47], v[0:3], v[116:119], v[32:47]
	v_mov_b64_e32 v[0:1], s[40:41]
	v_mov_b64_e32 v[2:3], s[42:43]
	v_mov_b64_e32 v[4:5], s[44:45]
	v_mov_b64_e32 v[6:7], s[46:47]
	v_mov_b64_e32 v[8:9], s[48:49]
	v_mov_b64_e32 v[10:11], s[50:51]
	v_mov_b64_e32 v[12:13], s[52:53]
	v_mfma_f32_32x32x16_bf16 v[32:47], v[58:61], v[112:115], v[32:47]
	v_mov_b64_e32 v[14:15], s[54:55]
	s_and_b32 s41, s91, 7
	s_waitcnt vmcnt(5)
	ds_write_b128 v204, v[136:139] offset:32768
	s_lshl_b32 s41, s41, 7
	s_or_b32 s62, s62, s41
	v_lshl_add_u64 v[178:179], s[62:63], 0, v[158:159]
	s_add_u32 s98, s22, s62
	s_addc_u32 s99, s23, s63
	s_add_u32 s98, s98, 0x40000
	s_addc_u32 s99, s99, 0
	s_add_u32 s100, s22, s64
	s_addc_u32 s101, s23, s65
	s_add_u32 s100, s100, 0x4000
	s_addc_u32 s101, s101, 0
	v_add_u32_e32 v240, 0x2a800000, v158
	v_add_u32_e32 v241, 0x26800000, v158
	v_add_u32_e32 v242, 0x2e800000, v154
	v_add_u32_e32 v243, 0x10000, v206
	v_add_u32_e32 v244, 0x10000, v207
	v_add_u32_e32 v245, 0x10000, v208
	v_add_u32_e32 v246, 0x10000, v209
	v_add_u32_e32 v247, 0x10000, v210
	v_add_u32_e32 v248, 0x10000, v211
	v_add_u32_e32 v249, 0x10000, v201
	v_add_u32_e32 v250, 0x10000, v202
	s_nop 4
	v_max_f32_e32 v48, v33, v33
	v_max_f32_e32 v49, v32, v32
	s_waitcnt lgkmcnt(1)
	v_mfma_f32_32x32x16_bf16 v[16:31], v[50:53], v[112:115], v[16:31]
	v_max_f32_e32 v48, v49, v48
	v_max3_f32 v48, v48, v34, v35
	v_max3_f32 v48, v48, v36, v37
	v_max3_f32 v48, v48, v38, v39
	v_max3_f32 v48, v48, v40, v41
	v_max3_f32 v48, v48, v42, v43
	v_max3_f32 v48, v48, v44, v45
	v_max3_f32 v48, v48, v46, v47
	s_nop 3
	v_max3_f32 v48, v48, v16, v17
	v_max3_f32 v48, v48, v18, v19
	v_max3_f32 v48, v48, v20, v21
	v_max3_f32 v48, v48, v22, v23
	v_max3_f32 v48, v48, v24, v25
	v_max3_f32 v48, v48, v26, v27
	v_max3_f32 v48, v48, v28, v29
	v_max3_f32 v48, v48, v30, v31
	v_mov_b32_e32 v49, v48
	s_nop 1
	v_permlane32_swap_b32_e32 v48, v49
	v_max_f32_e32 v49, v49, v49
	v_max_f32_e32 v48, v48, v48
	v_max_f32_e32 v48, v48, v49
	v_sub_f32_e32 v64, v16, v48
	v_add_u32_e32 v16, s83, v201
	v_sub_f32_e32 v49, v32, v48
	v_sub_f32_e32 v33, v33, v48
	v_sub_f32_e32 v34, v34, v48
	v_sub_f32_e32 v35, v35, v48
	v_sub_f32_e32 v36, v36, v48
	v_sub_f32_e32 v37, v37, v48
	v_sub_f32_e32 v38, v38, v48
	v_sub_f32_e32 v39, v39, v48
	v_sub_f32_e32 v40, v40, v48
	v_sub_f32_e32 v41, v41, v48
	v_sub_f32_e32 v42, v42, v48
	v_sub_f32_e32 v43, v43, v48
	v_sub_f32_e32 v44, v44, v48
	v_sub_f32_e32 v45, v45, v48
	v_sub_f32_e32 v46, v46, v48
	v_sub_f32_e32 v47, v47, v48
	s_waitcnt vmcnt(4)
	ds_write_b128 v16, v[140:143]
	v_add_u32_e32 v16, s83, v202
	v_exp_f32_e32 v194, v49
	v_exp_f32_e32 v216, v33
	v_exp_f32_e32 v192, v34
	v_exp_f32_e32 v195, v35
	v_exp_f32_e32 v190, v36
	v_exp_f32_e32 v193, v37
	v_exp_f32_e32 v189, v38
	v_exp_f32_e32 v191, v39
	v_exp_f32_e32 v186, v40
	v_exp_f32_e32 v188, v41
	v_exp_f32_e32 v185, v42
	v_exp_f32_e32 v187, v43
	v_exp_f32_e32 v181, v44
	v_exp_f32_e32 v183, v45
	v_exp_f32_e32 v180, v46
	v_exp_f32_e32 v182, v47
	s_waitcnt vmcnt(3)
	ds_write_b64 v16, v[172:173]
	v_add_f32_e32 v161, 0, v48
	s_waitcnt lgkmcnt(0)
	s_barrier
	v_sub_f32_e32 v79, v31, v48
	v_sub_f32_e32 v78, v30, v48
	v_sub_f32_e32 v77, v29, v48
	v_sub_f32_e32 v76, v28, v48
	v_sub_f32_e32 v75, v27, v48
	v_sub_f32_e32 v74, v26, v48
	v_sub_f32_e32 v73, v25, v48
	v_sub_f32_e32 v72, v24, v48
	v_sub_f32_e32 v71, v23, v48
	v_sub_f32_e32 v70, v22, v48
	v_sub_f32_e32 v69, v21, v48
	v_sub_f32_e32 v68, v20, v48
	v_sub_f32_e32 v67, v19, v48
	v_sub_f32_e32 v66, v18, v48
	v_sub_f32_e32 v65, v17, v48
	v_xor_b32_e32 v32, 0x80000000, v161
	v_mov_b64_e32 v[30:31], v[14:15]
	v_mov_b64_e32 v[28:29], v[12:13]
	v_mov_b64_e32 v[26:27], v[10:11]
	v_mov_b64_e32 v[24:25], v[8:9]
	v_mov_b64_e32 v[22:23], v[6:7]
	v_mov_b64_e32 v[20:21], v[4:5]
	v_mov_b64_e32 v[18:19], v[2:3]
	v_mov_b64_e32 v[16:17], v[0:1]
	v_mov_b32_e32 v33, v32
	v_mov_b32_e32 v34, v32
	v_mov_b32_e32 v35, v32
	v_mov_b32_e32 v36, v32
	v_mov_b32_e32 v37, v32
	v_mov_b32_e32 v38, v32
	v_mov_b32_e32 v39, v32
	v_mov_b32_e32 v40, v32
	v_mov_b32_e32 v41, v32
	v_mov_b32_e32 v42, v32
	v_mov_b32_e32 v43, v32
	v_mov_b32_e32 v44, v32
	v_mov_b32_e32 v45, v32
	v_mov_b32_e32 v46, v32
	v_mov_b32_e32 v47, v32
	.p2align	6
